# K-loop heads aligned to 64 bytes
# baseline (speedup 1.0000x reference)
.LBB0_91:
	s_ashr_i32 s53, s52, 31
	s_lshl_b64 s[10:11], s[52:53], 19
	s_add_u32 s54, s68, s10
	s_addc_u32 s55, s69, s11
	s_and_b64 s[10:11], s[40:41], exec
	s_cselect_b32 s5, s55, s7
	s_cselect_b32 s24, s54, s6
	s_ashr_i32 s51, s50, 31
	s_lshl_b64 s[10:11], s[50:51], 19
	s_add_u32 s56, s15, s10
	s_addc_u32 s57, s26, s11
	s_and_b64 s[10:11], s[40:41], exec
	s_cselect_b32 s47, s57, s9
	s_cselect_b32 s51, s56, s8
	s_add_u32 s6, s6, 0x40080
	s_addc_u32 s7, s7, 0
	s_add_u32 s53, s8, 0x100
	v_mov_b32_e32 v0, 0
	v_mov_b32_e32 v251, 0x260
	v_mov_b32_e32 v224, 0x3e124925
	v_mov_b32_e32 v223, 0x3e2aaaab
	v_mov_b32_e32 v222, 0x3e4ccccd
	v_mov_b32_e32 v221, 0x3e800000
	v_mov_b32_e32 v220, 0x3eaaaaab
	s_addc_u32 s58, s9, 0
	s_mov_b32 s59, -2
	v_mov_b32_e32 v1, v0
	v_mov_b32_e32 v2, v0
	v_mov_b32_e32 v3, v0
	v_mov_b32_e32 v4, v0
	v_mov_b32_e32 v5, v0
	v_mov_b32_e32 v6, v0
	v_mov_b32_e32 v7, v0
	v_mov_b32_e32 v16, v0
	v_mov_b32_e32 v17, v0
	v_mov_b32_e32 v18, v0
	v_mov_b32_e32 v19, v0
	v_mov_b32_e32 v20, v0
	v_mov_b32_e32 v21, v0
	v_mov_b32_e32 v22, v0
	v_mov_b32_e32 v23, v0
	v_mov_b32_e32 v32, v0
	v_mov_b32_e32 v33, v0
	v_mov_b32_e32 v34, v0
	v_mov_b32_e32 v35, v0
	v_mov_b32_e32 v36, v0
	v_mov_b32_e32 v37, v0
	v_mov_b32_e32 v38, v0
	v_mov_b32_e32 v39, v0
	v_mov_b32_e32 v48, v0
	v_mov_b32_e32 v49, v0
	v_mov_b32_e32 v50, v0
	v_mov_b32_e32 v51, v0
	v_mov_b32_e32 v52, v0
	v_mov_b32_e32 v53, v0
	v_mov_b32_e32 v54, v0
	v_mov_b32_e32 v55, v0
	v_mov_b32_e32 v8, v0
	v_mov_b32_e32 v9, v0
	v_mov_b32_e32 v10, v0
	v_mov_b32_e32 v11, v0
	v_mov_b32_e32 v12, v0
	v_mov_b32_e32 v13, v0
	v_mov_b32_e32 v14, v0
	v_mov_b32_e32 v15, v0
	v_mov_b32_e32 v24, v0
	v_mov_b32_e32 v25, v0
	v_mov_b32_e32 v26, v0
	v_mov_b32_e32 v27, v0
	v_mov_b32_e32 v28, v0
	v_mov_b32_e32 v29, v0
	v_mov_b32_e32 v30, v0
	v_mov_b32_e32 v31, v0
	v_mov_b32_e32 v40, v0
	v_mov_b32_e32 v41, v0
	v_mov_b32_e32 v42, v0
	v_mov_b32_e32 v43, v0
	v_mov_b32_e32 v44, v0
	v_mov_b32_e32 v45, v0
	v_mov_b32_e32 v46, v0
	v_mov_b32_e32 v47, v0
	v_mov_b32_e32 v56, v0
	v_mov_b32_e32 v57, v0
	v_mov_b32_e32 v58, v0
	v_mov_b32_e32 v59, v0
	v_mov_b32_e32 v60, v0
	v_mov_b32_e32 v61, v0
	v_mov_b32_e32 v62, v0
	v_mov_b32_e32 v63, v0
	v_mov_b32_e32 v64, v0
	v_mov_b32_e32 v65, v0
	v_mov_b32_e32 v66, v0
	v_mov_b32_e32 v67, v0
	v_mov_b32_e32 v68, v0
	v_mov_b32_e32 v69, v0
	v_mov_b32_e32 v70, v0
	v_mov_b32_e32 v71, v0
	v_mov_b32_e32 v80, v0
	v_mov_b32_e32 v81, v0
	v_mov_b32_e32 v82, v0
	v_mov_b32_e32 v83, v0
	v_mov_b32_e32 v84, v0
	v_mov_b32_e32 v85, v0
	v_mov_b32_e32 v86, v0
	v_mov_b32_e32 v87, v0
	v_mov_b32_e32 v96, v0
	v_mov_b32_e32 v97, v0
	v_mov_b32_e32 v98, v0
	v_mov_b32_e32 v99, v0
	v_mov_b32_e32 v100, v0
	v_mov_b32_e32 v101, v0
	v_mov_b32_e32 v102, v0
	v_mov_b32_e32 v103, v0
	v_mov_b32_e32 v112, v0
	v_mov_b32_e32 v113, v0
	v_mov_b32_e32 v114, v0
	v_mov_b32_e32 v115, v0
	v_mov_b32_e32 v116, v0
	v_mov_b32_e32 v117, v0
	v_mov_b32_e32 v118, v0
	v_mov_b32_e32 v119, v0
	v_mov_b32_e32 v72, v0
	v_mov_b32_e32 v73, v0
	v_mov_b32_e32 v74, v0
	v_mov_b32_e32 v75, v0
	v_mov_b32_e32 v76, v0
	v_mov_b32_e32 v77, v0
	v_mov_b32_e32 v78, v0
	v_mov_b32_e32 v79, v0
	v_mov_b32_e32 v88, v0
	v_mov_b32_e32 v89, v0
	v_mov_b32_e32 v90, v0
	v_mov_b32_e32 v91, v0
	v_mov_b32_e32 v92, v0
	v_mov_b32_e32 v93, v0
	v_mov_b32_e32 v94, v0
	v_mov_b32_e32 v95, v0
	v_mov_b32_e32 v104, v0
	v_mov_b32_e32 v105, v0
	v_mov_b32_e32 v106, v0
	v_mov_b32_e32 v107, v0
	v_mov_b32_e32 v108, v0
	v_mov_b32_e32 v109, v0
	v_mov_b32_e32 v110, v0
	v_mov_b32_e32 v111, v0
	v_mov_b32_e32 v120, v0
	v_mov_b32_e32 v121, v0
	v_mov_b32_e32 v122, v0
	v_mov_b32_e32 v123, v0
	v_mov_b32_e32 v124, v0
	v_mov_b32_e32 v125, v0
	v_mov_b32_e32 v126, v0
	v_mov_b32_e32 v127, v0
	.p2align 6

.LBB0_146:
	s_ashr_i32 s55, s54, 31
	s_lshl_b64 s[10:11], s[54:55], 19
	s_add_u32 s56, s86, s10
	s_addc_u32 s57, s87, s11
	s_and_b64 s[10:11], s[40:41], exec
	s_cselect_b32 s24, s57, s7
	s_cselect_b32 s38, s56, s6
	s_ashr_i32 s58, s54, 4
	s_ashr_i32 s53, s52, 31
	s_ashr_i32 s59, s58, 31
	s_lshl_b64 s[10:11], s[52:53], 19
	s_lshl_b64 s[58:59], s[58:59], 21
	s_add_u32 s10, s16, s10
	s_addc_u32 s11, s17, s11
	s_add_u32 s58, s10, s58
	s_addc_u32 s59, s11, s59
	s_and_b64 s[10:11], s[40:41], exec
	s_cselect_b32 s53, s59, s9
	s_cselect_b32 s55, s58, s8
	s_add_u32 s6, s6, 0x40080
	s_addc_u32 s7, s7, 0
	s_add_u32 s60, s8, 0x100
	v_mov_b32_e32 v0, 0
	v_mov_b32_e32 v251, 0x260
	v_mov_b32_e32 v220, 0x3e124925
	v_mov_b32_e32 v219, 0x3e2aaaab
	v_mov_b32_e32 v218, 0x3e4ccccd
	v_mov_b32_e32 v217, 0x3e800000
	v_mov_b32_e32 v216, 0x3eaaaaab
	s_addc_u32 s61, s9, 0
	s_mov_b32 s74, -2
	v_mov_b32_e32 v1, v0
	v_mov_b32_e32 v2, v0
	v_mov_b32_e32 v3, v0
	v_mov_b32_e32 v4, v0
	v_mov_b32_e32 v5, v0
	v_mov_b32_e32 v6, v0
	v_mov_b32_e32 v7, v0
	v_mov_b32_e32 v16, v0
	v_mov_b32_e32 v17, v0
	v_mov_b32_e32 v18, v0
	v_mov_b32_e32 v19, v0
	v_mov_b32_e32 v20, v0
	v_mov_b32_e32 v21, v0
	v_mov_b32_e32 v22, v0
	v_mov_b32_e32 v23, v0
	v_mov_b32_e32 v32, v0
	v_mov_b32_e32 v33, v0
	v_mov_b32_e32 v34, v0
	v_mov_b32_e32 v35, v0
	v_mov_b32_e32 v36, v0
	v_mov_b32_e32 v37, v0
	v_mov_b32_e32 v38, v0
	v_mov_b32_e32 v39, v0
	v_mov_b32_e32 v48, v0
	v_mov_b32_e32 v49, v0
	v_mov_b32_e32 v50, v0
	v_mov_b32_e32 v51, v0
	v_mov_b32_e32 v52, v0
	v_mov_b32_e32 v53, v0
	v_mov_b32_e32 v54, v0
	v_mov_b32_e32 v55, v0
	v_mov_b32_e32 v8, v0
	v_mov_b32_e32 v9, v0
	v_mov_b32_e32 v10, v0
	v_mov_b32_e32 v11, v0
	v_mov_b32_e32 v12, v0
	v_mov_b32_e32 v13, v0
	v_mov_b32_e32 v14, v0
	v_mov_b32_e32 v15, v0
	v_mov_b32_e32 v24, v0
	v_mov_b32_e32 v25, v0
	v_mov_b32_e32 v26, v0
	v_mov_b32_e32 v27, v0
	v_mov_b32_e32 v28, v0
	v_mov_b32_e32 v29, v0
	v_mov_b32_e32 v30, v0
	v_mov_b32_e32 v31, v0
	v_mov_b32_e32 v40, v0
	v_mov_b32_e32 v41, v0
	v_mov_b32_e32 v42, v0
	v_mov_b32_e32 v43, v0
	v_mov_b32_e32 v44, v0
	v_mov_b32_e32 v45, v0
	v_mov_b32_e32 v46, v0
	v_mov_b32_e32 v47, v0
	v_mov_b32_e32 v56, v0
	v_mov_b32_e32 v57, v0
	v_mov_b32_e32 v58, v0
	v_mov_b32_e32 v59, v0
	v_mov_b32_e32 v60, v0
	v_mov_b32_e32 v61, v0
	v_mov_b32_e32 v62, v0
	v_mov_b32_e32 v63, v0
	v_mov_b32_e32 v64, v0
	v_mov_b32_e32 v65, v0
	v_mov_b32_e32 v66, v0
	v_mov_b32_e32 v67, v0
	v_mov_b32_e32 v68, v0
	v_mov_b32_e32 v69, v0
	v_mov_b32_e32 v70, v0
	v_mov_b32_e32 v71, v0
	v_mov_b32_e32 v80, v0
	v_mov_b32_e32 v81, v0
	v_mov_b32_e32 v82, v0
	v_mov_b32_e32 v83, v0
	v_mov_b32_e32 v84, v0
	v_mov_b32_e32 v85, v0
	v_mov_b32_e32 v86, v0
	v_mov_b32_e32 v87, v0
	v_mov_b32_e32 v96, v0
	v_mov_b32_e32 v97, v0
	v_mov_b32_e32 v98, v0
	v_mov_b32_e32 v99, v0
	v_mov_b32_e32 v100, v0
	v_mov_b32_e32 v101, v0
	v_mov_b32_e32 v102, v0
	v_mov_b32_e32 v103, v0
	v_mov_b32_e32 v112, v0
	v_mov_b32_e32 v113, v0
	v_mov_b32_e32 v114, v0
	v_mov_b32_e32 v115, v0
	v_mov_b32_e32 v116, v0
	v_mov_b32_e32 v117, v0
	v_mov_b32_e32 v118, v0
	v_mov_b32_e32 v119, v0
	v_mov_b32_e32 v72, v0
	v_mov_b32_e32 v73, v0
	v_mov_b32_e32 v74, v0
	v_mov_b32_e32 v75, v0
	v_mov_b32_e32 v76, v0
	v_mov_b32_e32 v77, v0
	v_mov_b32_e32 v78, v0
	v_mov_b32_e32 v79, v0
	v_mov_b32_e32 v88, v0
	v_mov_b32_e32 v89, v0
	v_mov_b32_e32 v90, v0
	v_mov_b32_e32 v91, v0
	v_mov_b32_e32 v92, v0
	v_mov_b32_e32 v93, v0
	v_mov_b32_e32 v94, v0
	v_mov_b32_e32 v95, v0
	v_mov_b32_e32 v104, v0
	v_mov_b32_e32 v105, v0
	v_mov_b32_e32 v106, v0
	v_mov_b32_e32 v107, v0
	v_mov_b32_e32 v108, v0
	v_mov_b32_e32 v109, v0
	v_mov_b32_e32 v110, v0
	v_mov_b32_e32 v111, v0
	v_mov_b32_e32 v120, v0
	v_mov_b32_e32 v121, v0
	v_mov_b32_e32 v122, v0
	v_mov_b32_e32 v123, v0
	v_mov_b32_e32 v124, v0
	v_mov_b32_e32 v125, v0
	v_mov_b32_e32 v126, v0
	v_mov_b32_e32 v127, v0
	.p2align 6

.LBB0_233:
	s_ashr_i32 s53, s52, 31
	s_lshl_b64 s[4:5], s[52:53], 19
	s_add_u32 s54, s68, s4
	s_addc_u32 s55, s69, s5
	s_and_b64 s[4:5], s[40:41], exec
	s_cselect_b32 s4, s55, s7
	s_cselect_b32 s5, s54, s6
	s_ashr_i32 s42, s52, 4
	s_ashr_i32 s51, s50, 31
	s_ashr_i32 s43, s42, 31
	s_lshl_b64 s[10:11], s[50:51], 19
	s_lshl_b64 s[42:43], s[42:43], 21
	s_add_u32 s10, s81, s10
	s_addc_u32 s11, s25, s11
	s_add_u32 s56, s10, s42
	s_addc_u32 s57, s11, s43
	s_and_b64 s[10:11], s[40:41], exec
	s_cselect_b32 s24, s57, s9
	s_cselect_b32 s42, s56, s8
	s_add_u32 s6, s6, 0x40080
	s_addc_u32 s7, s7, 0
	s_add_u32 s43, s8, 0x100
	v_mov_b32_e32 v0, 0
	v_mov_b32_e32 v251, 0x260
	v_mov_b32_e32 v222, 0x3e124925
	v_mov_b32_e32 v221, 0x3e2aaaab
	v_mov_b32_e32 v220, 0x3e4ccccd
	v_mov_b32_e32 v219, 0x3e800000
	v_mov_b32_e32 v218, 0x3eaaaaab
	s_addc_u32 s51, s9, 0
	s_mov_b32 s53, -2
	v_mov_b32_e32 v1, v0
	v_mov_b32_e32 v2, v0
	v_mov_b32_e32 v3, v0
	v_mov_b32_e32 v4, v0
	v_mov_b32_e32 v5, v0
	v_mov_b32_e32 v6, v0
	v_mov_b32_e32 v7, v0
	v_mov_b32_e32 v16, v0
	v_mov_b32_e32 v17, v0
	v_mov_b32_e32 v18, v0
	v_mov_b32_e32 v19, v0
	v_mov_b32_e32 v20, v0
	v_mov_b32_e32 v21, v0
	v_mov_b32_e32 v22, v0
	v_mov_b32_e32 v23, v0
	v_mov_b32_e32 v32, v0
	v_mov_b32_e32 v33, v0
	v_mov_b32_e32 v34, v0
	v_mov_b32_e32 v35, v0
	v_mov_b32_e32 v36, v0
	v_mov_b32_e32 v37, v0
	v_mov_b32_e32 v38, v0
	v_mov_b32_e32 v39, v0
	v_mov_b32_e32 v48, v0
	v_mov_b32_e32 v49, v0
	v_mov_b32_e32 v50, v0
	v_mov_b32_e32 v51, v0
	v_mov_b32_e32 v52, v0
	v_mov_b32_e32 v53, v0
	v_mov_b32_e32 v54, v0
	v_mov_b32_e32 v55, v0
	v_mov_b32_e32 v8, v0
	v_mov_b32_e32 v9, v0
	v_mov_b32_e32 v10, v0
	v_mov_b32_e32 v11, v0
	v_mov_b32_e32 v12, v0
	v_mov_b32_e32 v13, v0
	v_mov_b32_e32 v14, v0
	v_mov_b32_e32 v15, v0
	v_mov_b32_e32 v24, v0
	v_mov_b32_e32 v25, v0
	v_mov_b32_e32 v26, v0
	v_mov_b32_e32 v27, v0
	v_mov_b32_e32 v28, v0
	v_mov_b32_e32 v29, v0
	v_mov_b32_e32 v30, v0
	v_mov_b32_e32 v31, v0
	v_mov_b32_e32 v40, v0
	v_mov_b32_e32 v41, v0
	v_mov_b32_e32 v42, v0
	v_mov_b32_e32 v43, v0
	v_mov_b32_e32 v44, v0
	v_mov_b32_e32 v45, v0
	v_mov_b32_e32 v46, v0
	v_mov_b32_e32 v47, v0
	v_mov_b32_e32 v56, v0
	v_mov_b32_e32 v57, v0
	v_mov_b32_e32 v58, v0
	v_mov_b32_e32 v59, v0
	v_mov_b32_e32 v60, v0
	v_mov_b32_e32 v61, v0
	v_mov_b32_e32 v62, v0
	v_mov_b32_e32 v63, v0
	v_mov_b32_e32 v64, v0
	v_mov_b32_e32 v65, v0
	v_mov_b32_e32 v66, v0
	v_mov_b32_e32 v67, v0
	v_mov_b32_e32 v68, v0
	v_mov_b32_e32 v69, v0
	v_mov_b32_e32 v70, v0
	v_mov_b32_e32 v71, v0
	v_mov_b32_e32 v80, v0
	v_mov_b32_e32 v81, v0
	v_mov_b32_e32 v82, v0
	v_mov_b32_e32 v83, v0
	v_mov_b32_e32 v84, v0
	v_mov_b32_e32 v85, v0
	v_mov_b32_e32 v86, v0
	v_mov_b32_e32 v87, v0
	v_mov_b32_e32 v96, v0
	v_mov_b32_e32 v97, v0
	v_mov_b32_e32 v98, v0
	v_mov_b32_e32 v99, v0
	v_mov_b32_e32 v100, v0
	v_mov_b32_e32 v101, v0
	v_mov_b32_e32 v102, v0
	v_mov_b32_e32 v103, v0
	v_mov_b32_e32 v112, v0
	v_mov_b32_e32 v113, v0
	v_mov_b32_e32 v114, v0
	v_mov_b32_e32 v115, v0
	v_mov_b32_e32 v116, v0
	v_mov_b32_e32 v117, v0
	v_mov_b32_e32 v118, v0
	v_mov_b32_e32 v119, v0
	v_mov_b32_e32 v72, v0
	v_mov_b32_e32 v73, v0
	v_mov_b32_e32 v74, v0
	v_mov_b32_e32 v75, v0
	v_mov_b32_e32 v76, v0
	v_mov_b32_e32 v77, v0
	v_mov_b32_e32 v78, v0
	v_mov_b32_e32 v79, v0
	v_mov_b32_e32 v88, v0
	v_mov_b32_e32 v89, v0
	v_mov_b32_e32 v90, v0
	v_mov_b32_e32 v91, v0
	v_mov_b32_e32 v92, v0
	v_mov_b32_e32 v93, v0
	v_mov_b32_e32 v94, v0
	v_mov_b32_e32 v95, v0
	v_mov_b32_e32 v104, v0
	v_mov_b32_e32 v105, v0
	v_mov_b32_e32 v106, v0
	v_mov_b32_e32 v107, v0
	v_mov_b32_e32 v108, v0
	v_mov_b32_e32 v109, v0
	v_mov_b32_e32 v110, v0
	v_mov_b32_e32 v111, v0
	v_mov_b32_e32 v120, v0
	v_mov_b32_e32 v121, v0
	v_mov_b32_e32 v122, v0
	v_mov_b32_e32 v123, v0
	v_mov_b32_e32 v124, v0
	v_mov_b32_e32 v125, v0
	v_mov_b32_e32 v126, v0
	v_mov_b32_e32 v127, v0
	.p2align 6

.LBB0_332:
	s_add_u32 s24, s6, 0x100
	s_addc_u32 s38, s7, 0
	s_add_u32 s6, s8, 0x8000
	v_mov_b32_e32 v0, 0
	s_addc_u32 s7, s9, 0
	s_mov_b32 s8, 0
	v_mov_b32_e32 v1, v0
	v_mov_b32_e32 v2, v0
	v_mov_b32_e32 v3, v0
	v_mov_b32_e32 v4, v0
	v_mov_b32_e32 v5, v0
	v_mov_b32_e32 v6, v0
	v_mov_b32_e32 v7, v0
	v_mov_b32_e32 v16, v0
	v_mov_b32_e32 v17, v0
	v_mov_b32_e32 v18, v0
	v_mov_b32_e32 v19, v0
	v_mov_b32_e32 v20, v0
	v_mov_b32_e32 v21, v0
	v_mov_b32_e32 v22, v0
	v_mov_b32_e32 v23, v0
	v_mov_b32_e32 v32, v0
	v_mov_b32_e32 v33, v0
	v_mov_b32_e32 v34, v0
	v_mov_b32_e32 v35, v0
	v_mov_b32_e32 v36, v0
	v_mov_b32_e32 v37, v0
	v_mov_b32_e32 v38, v0
	v_mov_b32_e32 v39, v0
	v_mov_b32_e32 v48, v0
	v_mov_b32_e32 v49, v0
	v_mov_b32_e32 v50, v0
	v_mov_b32_e32 v51, v0
	v_mov_b32_e32 v52, v0
	v_mov_b32_e32 v53, v0
	v_mov_b32_e32 v54, v0
	v_mov_b32_e32 v55, v0
	v_mov_b32_e32 v8, v0
	v_mov_b32_e32 v9, v0
	v_mov_b32_e32 v10, v0
	v_mov_b32_e32 v11, v0
	v_mov_b32_e32 v12, v0
	v_mov_b32_e32 v13, v0
	v_mov_b32_e32 v14, v0
	v_mov_b32_e32 v15, v0
	v_mov_b32_e32 v24, v0
	v_mov_b32_e32 v25, v0
	v_mov_b32_e32 v26, v0
	v_mov_b32_e32 v27, v0
	v_mov_b32_e32 v28, v0
	v_mov_b32_e32 v29, v0
	v_mov_b32_e32 v30, v0
	v_mov_b32_e32 v31, v0
	v_mov_b32_e32 v40, v0
	v_mov_b32_e32 v41, v0
	v_mov_b32_e32 v42, v0
	v_mov_b32_e32 v43, v0
	v_mov_b32_e32 v44, v0
	v_mov_b32_e32 v45, v0
	v_mov_b32_e32 v46, v0
	v_mov_b32_e32 v47, v0
	v_mov_b32_e32 v56, v0
	v_mov_b32_e32 v57, v0
	v_mov_b32_e32 v58, v0
	v_mov_b32_e32 v59, v0
	v_mov_b32_e32 v60, v0
	v_mov_b32_e32 v61, v0
	v_mov_b32_e32 v62, v0
	v_mov_b32_e32 v63, v0
	v_mov_b32_e32 v64, v0
	v_mov_b32_e32 v65, v0
	v_mov_b32_e32 v66, v0
	v_mov_b32_e32 v67, v0
	v_mov_b32_e32 v68, v0
	v_mov_b32_e32 v69, v0
	v_mov_b32_e32 v70, v0
	v_mov_b32_e32 v71, v0
	v_mov_b32_e32 v80, v0
	v_mov_b32_e32 v81, v0
	v_mov_b32_e32 v82, v0
	v_mov_b32_e32 v83, v0
	v_mov_b32_e32 v84, v0
	v_mov_b32_e32 v85, v0
	v_mov_b32_e32 v86, v0
	v_mov_b32_e32 v87, v0
	v_mov_b32_e32 v96, v0
	v_mov_b32_e32 v97, v0
	v_mov_b32_e32 v98, v0
	v_mov_b32_e32 v99, v0
	v_mov_b32_e32 v100, v0
	v_mov_b32_e32 v101, v0
	v_mov_b32_e32 v102, v0
	v_mov_b32_e32 v103, v0
	v_mov_b32_e32 v112, v0
	v_mov_b32_e32 v113, v0
	v_mov_b32_e32 v114, v0
	v_mov_b32_e32 v115, v0
	v_mov_b32_e32 v116, v0
	v_mov_b32_e32 v117, v0
	v_mov_b32_e32 v118, v0
	v_mov_b32_e32 v119, v0
	v_mov_b32_e32 v72, v0
	v_mov_b32_e32 v73, v0
	v_mov_b32_e32 v74, v0
	v_mov_b32_e32 v75, v0
	v_mov_b32_e32 v76, v0
	v_mov_b32_e32 v77, v0
	v_mov_b32_e32 v78, v0
	v_mov_b32_e32 v79, v0
	v_mov_b32_e32 v88, v0
	v_mov_b32_e32 v89, v0
	v_mov_b32_e32 v90, v0
	v_mov_b32_e32 v91, v0
	v_mov_b32_e32 v92, v0
	v_mov_b32_e32 v93, v0
	v_mov_b32_e32 v94, v0
	v_mov_b32_e32 v95, v0
	v_mov_b32_e32 v104, v0
	v_mov_b32_e32 v105, v0
	v_mov_b32_e32 v106, v0
	v_mov_b32_e32 v107, v0
	v_mov_b32_e32 v108, v0
	v_mov_b32_e32 v109, v0
	v_mov_b32_e32 v110, v0
	v_mov_b32_e32 v111, v0
	v_mov_b32_e32 v120, v0
	v_mov_b32_e32 v121, v0
	v_mov_b32_e32 v122, v0
	v_mov_b32_e32 v123, v0
	v_mov_b32_e32 v124, v0
	v_mov_b32_e32 v125, v0
	v_mov_b32_e32 v126, v0
	v_mov_b32_e32 v127, v0
	.p2align 6

.LBB0_374:
	s_add_u32 s6, s6, 0x80
	s_addc_u32 s7, s7, 0
	s_add_u32 s10, s8, 0x100
	v_mov_b32_e32 v0, 0
	s_addc_u32 s11, s9, 0
	s_mov_b32 s8, 0
	v_mov_b32_e32 v1, v0
	v_mov_b32_e32 v2, v0
	v_mov_b32_e32 v3, v0
	v_mov_b32_e32 v4, v0
	v_mov_b32_e32 v5, v0
	v_mov_b32_e32 v6, v0
	v_mov_b32_e32 v7, v0
	v_mov_b32_e32 v16, v0
	v_mov_b32_e32 v17, v0
	v_mov_b32_e32 v18, v0
	v_mov_b32_e32 v19, v0
	v_mov_b32_e32 v20, v0
	v_mov_b32_e32 v21, v0
	v_mov_b32_e32 v22, v0
	v_mov_b32_e32 v23, v0
	v_mov_b32_e32 v32, v0
	v_mov_b32_e32 v33, v0
	v_mov_b32_e32 v34, v0
	v_mov_b32_e32 v35, v0
	v_mov_b32_e32 v36, v0
	v_mov_b32_e32 v37, v0
	v_mov_b32_e32 v38, v0
	v_mov_b32_e32 v39, v0
	v_mov_b32_e32 v48, v0
	v_mov_b32_e32 v49, v0
	v_mov_b32_e32 v50, v0
	v_mov_b32_e32 v51, v0
	v_mov_b32_e32 v52, v0
	v_mov_b32_e32 v53, v0
	v_mov_b32_e32 v54, v0
	v_mov_b32_e32 v55, v0
	v_mov_b32_e32 v8, v0
	v_mov_b32_e32 v9, v0
	v_mov_b32_e32 v10, v0
	v_mov_b32_e32 v11, v0
	v_mov_b32_e32 v12, v0
	v_mov_b32_e32 v13, v0
	v_mov_b32_e32 v14, v0
	v_mov_b32_e32 v15, v0
	v_mov_b32_e32 v24, v0
	v_mov_b32_e32 v25, v0
	v_mov_b32_e32 v26, v0
	v_mov_b32_e32 v27, v0
	v_mov_b32_e32 v28, v0
	v_mov_b32_e32 v29, v0
	v_mov_b32_e32 v30, v0
	v_mov_b32_e32 v31, v0
	v_mov_b32_e32 v40, v0
	v_mov_b32_e32 v41, v0
	v_mov_b32_e32 v42, v0
	v_mov_b32_e32 v43, v0
	v_mov_b32_e32 v44, v0
	v_mov_b32_e32 v45, v0
	v_mov_b32_e32 v46, v0
	v_mov_b32_e32 v47, v0
	v_mov_b32_e32 v56, v0
	v_mov_b32_e32 v57, v0
	v_mov_b32_e32 v58, v0
	v_mov_b32_e32 v59, v0
	v_mov_b32_e32 v60, v0
	v_mov_b32_e32 v61, v0
	v_mov_b32_e32 v62, v0
	v_mov_b32_e32 v63, v0
	v_mov_b32_e32 v64, v0
	v_mov_b32_e32 v65, v0
	v_mov_b32_e32 v66, v0
	v_mov_b32_e32 v67, v0
	v_mov_b32_e32 v68, v0
	v_mov_b32_e32 v69, v0
	v_mov_b32_e32 v70, v0
	v_mov_b32_e32 v71, v0
	v_mov_b32_e32 v80, v0
	v_mov_b32_e32 v81, v0
	v_mov_b32_e32 v82, v0
	v_mov_b32_e32 v83, v0
	v_mov_b32_e32 v84, v0
	v_mov_b32_e32 v85, v0
	v_mov_b32_e32 v86, v0
	v_mov_b32_e32 v87, v0
	v_mov_b32_e32 v96, v0
	v_mov_b32_e32 v97, v0
	v_mov_b32_e32 v98, v0
	v_mov_b32_e32 v99, v0
	v_mov_b32_e32 v100, v0
	v_mov_b32_e32 v101, v0
	v_mov_b32_e32 v102, v0
	v_mov_b32_e32 v103, v0
	v_mov_b32_e32 v112, v0
	v_mov_b32_e32 v113, v0
	v_mov_b32_e32 v114, v0
	v_mov_b32_e32 v115, v0
	v_mov_b32_e32 v116, v0
	v_mov_b32_e32 v117, v0
	v_mov_b32_e32 v118, v0
	v_mov_b32_e32 v119, v0
	v_mov_b32_e32 v72, v0
	v_mov_b32_e32 v73, v0
	v_mov_b32_e32 v74, v0
	v_mov_b32_e32 v75, v0
	v_mov_b32_e32 v76, v0
	v_mov_b32_e32 v77, v0
	v_mov_b32_e32 v78, v0
	v_mov_b32_e32 v79, v0
	v_mov_b32_e32 v88, v0
	v_mov_b32_e32 v89, v0
	v_mov_b32_e32 v90, v0
	v_mov_b32_e32 v91, v0
	v_mov_b32_e32 v92, v0
	v_mov_b32_e32 v93, v0
	v_mov_b32_e32 v94, v0
	v_mov_b32_e32 v95, v0
	v_mov_b32_e32 v104, v0
	v_mov_b32_e32 v105, v0
	v_mov_b32_e32 v106, v0
	v_mov_b32_e32 v107, v0
	v_mov_b32_e32 v108, v0
	v_mov_b32_e32 v109, v0
	v_mov_b32_e32 v110, v0
	v_mov_b32_e32 v111, v0
	v_mov_b32_e32 v120, v0
	v_mov_b32_e32 v121, v0
	v_mov_b32_e32 v122, v0
	v_mov_b32_e32 v123, v0
	v_mov_b32_e32 v124, v0
	v_mov_b32_e32 v125, v0
	v_mov_b32_e32 v126, v0
	v_mov_b32_e32 v127, v0
	.p2align 6

.LBB0_551:
	s_ashr_i32 s51, s50, 31
	s_lshl_b64 s[4:5], s[50:51], 19
	s_add_u32 s52, s68, s4
	s_addc_u32 s53, s69, s5
	s_and_b64 s[4:5], s[40:41], exec
	s_cselect_b32 s4, s53, s7
	s_cselect_b32 s5, s52, s6
	s_ashr_i32 s47, s46, 31
	s_lshl_b64 s[10:11], s[46:47], 19
	s_add_u32 s54, s13, s10
	s_addc_u32 s55, s15, s11
	s_and_b64 s[10:11], s[40:41], exec
	s_cselect_b32 s24, s55, s9
	s_cselect_b32 s38, s54, s8
	s_add_u32 s6, s6, 0x40080
	s_addc_u32 s7, s7, 0
	s_add_u32 s47, s8, 0x100
	v_mov_b32_e32 v0, 0
	s_addc_u32 s51, s9, 0
	s_mov_b32 s56, -2
	v_mov_b32_e32 v1, v0
	v_mov_b32_e32 v2, v0
	v_mov_b32_e32 v3, v0
	v_mov_b32_e32 v4, v0
	v_mov_b32_e32 v5, v0
	v_mov_b32_e32 v6, v0
	v_mov_b32_e32 v7, v0
	v_mov_b32_e32 v16, v0
	v_mov_b32_e32 v17, v0
	v_mov_b32_e32 v18, v0
	v_mov_b32_e32 v19, v0
	v_mov_b32_e32 v20, v0
	v_mov_b32_e32 v21, v0
	v_mov_b32_e32 v22, v0
	v_mov_b32_e32 v23, v0
	v_mov_b32_e32 v32, v0
	v_mov_b32_e32 v33, v0
	v_mov_b32_e32 v34, v0
	v_mov_b32_e32 v35, v0
	v_mov_b32_e32 v36, v0
	v_mov_b32_e32 v37, v0
	v_mov_b32_e32 v38, v0
	v_mov_b32_e32 v39, v0
	v_mov_b32_e32 v48, v0
	v_mov_b32_e32 v49, v0
	v_mov_b32_e32 v50, v0
	v_mov_b32_e32 v51, v0
	v_mov_b32_e32 v52, v0
	v_mov_b32_e32 v53, v0
	v_mov_b32_e32 v54, v0
	v_mov_b32_e32 v55, v0
	v_mov_b32_e32 v8, v0
	v_mov_b32_e32 v9, v0
	v_mov_b32_e32 v10, v0
	v_mov_b32_e32 v11, v0
	v_mov_b32_e32 v12, v0
	v_mov_b32_e32 v13, v0
	v_mov_b32_e32 v14, v0
	v_mov_b32_e32 v15, v0
	v_mov_b32_e32 v24, v0
	v_mov_b32_e32 v25, v0
	v_mov_b32_e32 v26, v0
	v_mov_b32_e32 v27, v0
	v_mov_b32_e32 v28, v0
	v_mov_b32_e32 v29, v0
	v_mov_b32_e32 v30, v0
	v_mov_b32_e32 v31, v0
	v_mov_b32_e32 v40, v0
	v_mov_b32_e32 v41, v0
	v_mov_b32_e32 v42, v0
	v_mov_b32_e32 v43, v0
	v_mov_b32_e32 v44, v0
	v_mov_b32_e32 v45, v0
	v_mov_b32_e32 v46, v0
	v_mov_b32_e32 v47, v0
	v_mov_b32_e32 v56, v0
	v_mov_b32_e32 v57, v0
	v_mov_b32_e32 v58, v0
	v_mov_b32_e32 v59, v0
	v_mov_b32_e32 v60, v0
	v_mov_b32_e32 v61, v0
	v_mov_b32_e32 v62, v0
	v_mov_b32_e32 v63, v0
	v_mov_b32_e32 v64, v0
	v_mov_b32_e32 v65, v0
	v_mov_b32_e32 v66, v0
	v_mov_b32_e32 v67, v0
	v_mov_b32_e32 v68, v0
	v_mov_b32_e32 v69, v0
	v_mov_b32_e32 v70, v0
	v_mov_b32_e32 v71, v0
	v_mov_b32_e32 v80, v0
	v_mov_b32_e32 v81, v0
	v_mov_b32_e32 v82, v0
	v_mov_b32_e32 v83, v0
	v_mov_b32_e32 v84, v0
	v_mov_b32_e32 v85, v0
	v_mov_b32_e32 v86, v0
	v_mov_b32_e32 v87, v0
	v_mov_b32_e32 v96, v0
	v_mov_b32_e32 v97, v0
	v_mov_b32_e32 v98, v0
	v_mov_b32_e32 v99, v0
	v_mov_b32_e32 v100, v0
	v_mov_b32_e32 v101, v0
	v_mov_b32_e32 v102, v0
	v_mov_b32_e32 v103, v0
	v_mov_b32_e32 v112, v0
	v_mov_b32_e32 v113, v0
	v_mov_b32_e32 v114, v0
	v_mov_b32_e32 v115, v0
	v_mov_b32_e32 v116, v0
	v_mov_b32_e32 v117, v0
	v_mov_b32_e32 v118, v0
	v_mov_b32_e32 v119, v0
	v_mov_b32_e32 v72, v0
	v_mov_b32_e32 v73, v0
	v_mov_b32_e32 v74, v0
	v_mov_b32_e32 v75, v0
	v_mov_b32_e32 v76, v0
	v_mov_b32_e32 v77, v0
	v_mov_b32_e32 v78, v0
	v_mov_b32_e32 v79, v0
	v_mov_b32_e32 v88, v0
	v_mov_b32_e32 v89, v0
	v_mov_b32_e32 v90, v0
	v_mov_b32_e32 v91, v0
	v_mov_b32_e32 v92, v0
	v_mov_b32_e32 v93, v0
	v_mov_b32_e32 v94, v0
	v_mov_b32_e32 v95, v0
	v_mov_b32_e32 v104, v0
	v_mov_b32_e32 v105, v0
	v_mov_b32_e32 v106, v0
	v_mov_b32_e32 v107, v0
	v_mov_b32_e32 v108, v0
	v_mov_b32_e32 v109, v0
	v_mov_b32_e32 v110, v0
	v_mov_b32_e32 v111, v0
	v_mov_b32_e32 v120, v0
	v_mov_b32_e32 v121, v0
	v_mov_b32_e32 v122, v0
	v_mov_b32_e32 v123, v0
	v_mov_b32_e32 v124, v0
	v_mov_b32_e32 v125, v0
	v_mov_b32_e32 v126, v0
	v_mov_b32_e32 v127, v0
	.p2align 6

.LBB0_713:
	s_ashr_i32 s51, s50, 31
	s_lshl_b64 s[10:11], s[50:51], 19
	s_add_u32 s52, s15, s10
	s_addc_u32 s53, s16, s11
	s_and_b64 s[10:11], s[40:41], exec
	s_cselect_b32 s24, s53, s7
	s_cselect_b32 s51, s52, s6
	s_ashr_i32 s49, s48, 31
	s_lshl_b64 s[10:11], s[48:49], 19
	s_add_u32 s54, s12, s10
	s_addc_u32 s55, s13, s11
	s_and_b64 s[10:11], s[40:41], exec
	s_cselect_b32 s49, s55, s9
	s_cselect_b32 s56, s54, s8
	s_add_u32 s6, s6, 0x40080
	s_addc_u32 s7, s7, 0
	s_add_u32 s57, s8, 0x100
	v_mov_b32_e32 v0, 0
	s_addc_u32 s58, s9, 0
	s_mov_b32 s59, -2
	v_mov_b32_e32 v1, v0
	v_mov_b32_e32 v2, v0
	v_mov_b32_e32 v3, v0
	v_mov_b32_e32 v4, v0
	v_mov_b32_e32 v5, v0
	v_mov_b32_e32 v6, v0
	v_mov_b32_e32 v7, v0
	v_mov_b32_e32 v16, v0
	v_mov_b32_e32 v17, v0
	v_mov_b32_e32 v18, v0
	v_mov_b32_e32 v19, v0
	v_mov_b32_e32 v20, v0
	v_mov_b32_e32 v21, v0
	v_mov_b32_e32 v22, v0
	v_mov_b32_e32 v23, v0
	v_mov_b32_e32 v32, v0
	v_mov_b32_e32 v33, v0
	v_mov_b32_e32 v34, v0
	v_mov_b32_e32 v35, v0
	v_mov_b32_e32 v36, v0
	v_mov_b32_e32 v37, v0
	v_mov_b32_e32 v38, v0
	v_mov_b32_e32 v39, v0
	v_mov_b32_e32 v48, v0
	v_mov_b32_e32 v49, v0
	v_mov_b32_e32 v50, v0
	v_mov_b32_e32 v51, v0
	v_mov_b32_e32 v52, v0
	v_mov_b32_e32 v53, v0
	v_mov_b32_e32 v54, v0
	v_mov_b32_e32 v55, v0
	v_mov_b32_e32 v8, v0
	v_mov_b32_e32 v9, v0
	v_mov_b32_e32 v10, v0
	v_mov_b32_e32 v11, v0
	v_mov_b32_e32 v12, v0
	v_mov_b32_e32 v13, v0
	v_mov_b32_e32 v14, v0
	v_mov_b32_e32 v15, v0
	v_mov_b32_e32 v24, v0
	v_mov_b32_e32 v25, v0
	v_mov_b32_e32 v26, v0
	v_mov_b32_e32 v27, v0
	v_mov_b32_e32 v28, v0
	v_mov_b32_e32 v29, v0
	v_mov_b32_e32 v30, v0
	v_mov_b32_e32 v31, v0
	v_mov_b32_e32 v40, v0
	v_mov_b32_e32 v41, v0
	v_mov_b32_e32 v42, v0
	v_mov_b32_e32 v43, v0
	v_mov_b32_e32 v44, v0
	v_mov_b32_e32 v45, v0
	v_mov_b32_e32 v46, v0
	v_mov_b32_e32 v47, v0
	v_mov_b32_e32 v56, v0
	v_mov_b32_e32 v57, v0
	v_mov_b32_e32 v58, v0
	v_mov_b32_e32 v59, v0
	v_mov_b32_e32 v60, v0
	v_mov_b32_e32 v61, v0
	v_mov_b32_e32 v62, v0
	v_mov_b32_e32 v63, v0
	v_mov_b32_e32 v64, v0
	v_mov_b32_e32 v65, v0
	v_mov_b32_e32 v66, v0
	v_mov_b32_e32 v67, v0
	v_mov_b32_e32 v68, v0
	v_mov_b32_e32 v69, v0
	v_mov_b32_e32 v70, v0
	v_mov_b32_e32 v71, v0
	v_mov_b32_e32 v80, v0
	v_mov_b32_e32 v81, v0
	v_mov_b32_e32 v82, v0
	v_mov_b32_e32 v83, v0
	v_mov_b32_e32 v84, v0
	v_mov_b32_e32 v85, v0
	v_mov_b32_e32 v86, v0
	v_mov_b32_e32 v87, v0
	v_mov_b32_e32 v96, v0
	v_mov_b32_e32 v97, v0
	v_mov_b32_e32 v98, v0
	v_mov_b32_e32 v99, v0
	v_mov_b32_e32 v100, v0
	v_mov_b32_e32 v101, v0
	v_mov_b32_e32 v102, v0
	v_mov_b32_e32 v103, v0
	v_mov_b32_e32 v112, v0
	v_mov_b32_e32 v113, v0
	v_mov_b32_e32 v114, v0
	v_mov_b32_e32 v115, v0
	v_mov_b32_e32 v116, v0
	v_mov_b32_e32 v117, v0
	v_mov_b32_e32 v118, v0
	v_mov_b32_e32 v119, v0
	v_mov_b32_e32 v72, v0
	v_mov_b32_e32 v73, v0
	v_mov_b32_e32 v74, v0
	v_mov_b32_e32 v75, v0
	v_mov_b32_e32 v76, v0
	v_mov_b32_e32 v77, v0
	v_mov_b32_e32 v78, v0
	v_mov_b32_e32 v79, v0
	v_mov_b32_e32 v88, v0
	v_mov_b32_e32 v89, v0
	v_mov_b32_e32 v90, v0
	v_mov_b32_e32 v91, v0
	v_mov_b32_e32 v92, v0
	v_mov_b32_e32 v93, v0
	v_mov_b32_e32 v94, v0
	v_mov_b32_e32 v95, v0
	v_mov_b32_e32 v104, v0
	v_mov_b32_e32 v105, v0
	v_mov_b32_e32 v106, v0
	v_mov_b32_e32 v107, v0
	v_mov_b32_e32 v108, v0
	v_mov_b32_e32 v109, v0
	v_mov_b32_e32 v110, v0
	v_mov_b32_e32 v111, v0
	v_mov_b32_e32 v120, v0
	v_mov_b32_e32 v121, v0
	v_mov_b32_e32 v122, v0
	v_mov_b32_e32 v123, v0
	v_mov_b32_e32 v124, v0
	v_mov_b32_e32 v125, v0
	v_mov_b32_e32 v126, v0
	v_mov_b32_e32 v127, v0
	.p2align 6
